# comb2: + weight-transposes rebalanced (ATT0 keeps [192,608), GU0 idle half-round hosts [608,1040), QKV1 idle hosts [1040,1472))
# speedup vs baseline: 1.0178x; 1.0045x over previous
.LBB0_326:
	s_or_b64 exec, exec, s[4:5]
	v_readlane_b32 s0, v219, 9
	v_lshlrev_b32_e32 v20, 2, v149
	v_readlane_b32 s8, v219, 17
	v_readlane_b32 s9, v219, 18
	s_waitcnt lgkmcnt(0)
	s_barrier
	s_nop 2
	global_load_dword v0, v20, s[8:9]
	global_load_dword v1, v20, s[8:9] offset:256
	global_load_dword v2, v20, s[8:9] offset:512
	global_load_dword v3, v20, s[8:9] offset:768
	v_mbcnt_hi_u32_b32 v4, -1, v163
	v_and_b32_e32 v5, 64, v4
	v_xor_b32_e32 v6, 32, v4
	v_add_u32_e32 v5, 64, v5
	v_cmp_lt_i32_e32 vcc, v6, v5
	v_xor_b32_e32 v7, 16, v4
	v_xor_b32_e32 v8, 8, v4
	v_cndmask_b32_e32 v6, v4, v6, vcc
	v_lshlrev_b32_e32 v172, 2, v6
	v_cmp_lt_i32_e32 vcc, v7, v5
	v_xor_b32_e32 v9, 4, v4
	v_xor_b32_e32 v10, 2, v4
	v_cndmask_b32_e32 v7, v4, v7, vcc
	v_lshlrev_b32_e32 v173, 2, v7
	v_cmp_lt_i32_e32 vcc, v8, v5
	v_xor_b32_e32 v11, 1, v4
	s_bcnt1_i32_b32 s0, s78
	s_bitcmp0_b32 s0, 0
	s_cselect_b64 s[8:9], -1, 0
	v_readlane_b32 s1, v219, 10
	v_readlane_b32 s2, v219, 11
	v_readlane_b32 s3, v219, 12
	v_readlane_b32 s4, v219, 13
	v_readlane_b32 s5, v219, 14
	v_readlane_b32 s6, v219, 15
	v_readlane_b32 s7, v219, 16
	v_readlane_b32 s10, v219, 19
	v_readlane_b32 s11, v219, 20
	v_readlane_b32 s12, v219, 21
	v_readlane_b32 s13, v219, 22
	v_readlane_b32 s14, v219, 23
	v_readlane_b32 s15, v219, 24
	s_waitcnt vmcnt(2)
	v_mul_f32_e32 v6, v0, v1
	ds_bpermute_b32 v6, v172, v6
	s_waitcnt vmcnt(0)
	v_mul_f32_e32 v12, v2, v3
	ds_bpermute_b32 v12, v172, v12
	s_waitcnt lgkmcnt(1)
	v_fmac_f32_e32 v6, v0, v1
	ds_bpermute_b32 v0, v173, v6
	s_waitcnt lgkmcnt(1)
	v_fmac_f32_e32 v12, v2, v3
	ds_bpermute_b32 v1, v173, v12
	v_cndmask_b32_e32 v2, v4, v8, vcc
	v_lshlrev_b32_e32 v174, 2, v2
	s_waitcnt lgkmcnt(1)
	v_add_f32_e32 v0, v6, v0
	ds_bpermute_b32 v2, v174, v0
	s_waitcnt lgkmcnt(1)
	v_add_f32_e32 v1, v12, v1
	ds_bpermute_b32 v3, v174, v1
	v_cmp_lt_i32_e32 vcc, v9, v5
	s_waitcnt lgkmcnt(1)
	v_add_f32_e32 v0, v0, v2
	v_cndmask_b32_e32 v6, v4, v9, vcc
	v_lshlrev_b32_e32 v175, 2, v6
	s_waitcnt lgkmcnt(0)
	v_add_f32_e32 v1, v1, v3
	ds_bpermute_b32 v2, v175, v0
	ds_bpermute_b32 v3, v175, v1
	v_cmp_lt_i32_e32 vcc, v10, v5
	s_waitcnt lgkmcnt(1)
	v_add_f32_e32 v0, v0, v2
	v_cndmask_b32_e32 v6, v4, v10, vcc
	v_lshlrev_b32_e32 v176, 2, v6
	s_waitcnt lgkmcnt(0)
	v_add_f32_e32 v1, v1, v3
	ds_bpermute_b32 v2, v176, v0
	ds_bpermute_b32 v3, v176, v1
	v_cmp_lt_i32_e32 vcc, v11, v5
	s_waitcnt lgkmcnt(1)
	v_add_f32_e32 v21, v0, v2
	v_cndmask_b32_e32 v4, v4, v11, vcc
	v_lshlrev_b32_e32 v177, 2, v4
	s_waitcnt lgkmcnt(0)
	v_add_f32_e32 v22, v1, v3
	ds_bpermute_b32 v23, v177, v21
	ds_bpermute_b32 v24, v177, v22
	s_and_b64 vcc, exec, s[8:9]
	s_cbranch_vccnz .LBB0_347
	s_add_i32 s0, s78, 0xc0
	s_cmpk_gt_i32 s0, 0x25f
	s_waitcnt lgkmcnt(0)
	s_barrier
	s_cbranch_scc1 .LBB0_346
	s_movk_i32 s1, 0x2100
	v_lshrrev_b32_e32 v25, 3, v149
	v_and_b32_e32 v4, 56, v144
	s_cmpk_eq_i32 s58, 0x100
	v_mad_u32_u24 v1, v148, s1, 0
	v_lshrrev_b32_e32 v0, 5, v149
	v_and_b32_e32 v2, 31, v168
	v_mul_u32_u24_e32 v3, 0x84, v4
	v_lshlrev_b32_e32 v7, 2, v25
	s_cselect_b64 s[6:7], -1, 0
	v_mov_b32_e32 v5, 0
	v_lshl_add_u32 v6, v2, 2, v1
	s_movk_i32 s1, 0x84
	v_add3_u32 v26, v1, v3, v7
	v_or_b32_e32 v27, 8, v25
	v_or_b32_e32 v28, 16, v25
	v_or_b32_e32 v29, 24, v25
	v_mov_b32_e32 v1, v0
	s_movk_i32 s2, 0x187f
	s_movk_i32 s3, 0x1ff
	s_movk_i32 s10, 0xcff
	v_lshlrev_b32_e32 v8, 2, v2
	v_lshlrev_b32_e32 v10, 1, v4
	v_mov_b32_e32 v30, 0xffffe780
	v_mov_b32_e32 v31, 0xc00
	v_mov_b32_e32 v32, 0x600
	v_mov_b32_e32 v33, 0x2c0000
	v_mov_b32_e32 v34, 0x1400000
	v_mov_b32_e32 v35, 0x2980000
	v_mov_b32_e32 v36, 0x900000
	v_mov_b32_e32 v37, 0x1e80000
	v_mov_b32_e32 v38, 0x700000
	v_mov_b32_e32 v39, 0x1c80000
	v_mov_b32_e32 v40, 0x100000
	v_mov_b32_e32 v41, 0x1980000
	s_branch .LBB0_330
.LBB0_329:
	s_add_i32 s0, s0, s58
	s_cmpk_lt_i32 s0, 0x260
	s_cbranch_scc0 .LBB0_346

.LBB0_375:
	s_and_b64 vcc, exec, s[8:9]
	s_cbranch_vccz .LBB0_396
	s_add_i32 s0, s78, 0xc0
	s_cmpk_gt_i32 s0, 0x25f
	s_waitcnt lgkmcnt(0)
	s_barrier
	s_cbranch_scc1 .LBB0_395
	s_movk_i32 s1, 0x2100
	v_lshrrev_b32_e32 v20, 3, v149
	v_and_b32_e32 v4, 56, v144
	s_cmpk_eq_i32 s58, 0x100
	v_mad_u32_u24 v1, v148, s1, 0
	v_lshrrev_b32_e32 v0, 5, v149
	v_and_b32_e32 v2, 31, v168
	v_mul_u32_u24_e32 v3, 0x84, v4
	v_lshlrev_b32_e32 v7, 2, v20
	s_cselect_b64 s[6:7], -1, 0
	v_mov_b32_e32 v5, 0
	v_lshl_add_u32 v6, v2, 2, v1
	s_movk_i32 s1, 0x84
	v_add3_u32 v21, v1, v3, v7
	v_or_b32_e32 v22, 8, v20
	v_or_b32_e32 v23, 16, v20
	v_or_b32_e32 v24, 24, v20
	v_mov_b32_e32 v1, v0
	s_movk_i32 s2, 0x187f
	s_movk_i32 s3, 0x1ff
	s_movk_i32 s10, 0xcff
	v_lshlrev_b32_e32 v8, 2, v2
	v_lshlrev_b32_e32 v10, 1, v4
	v_mov_b32_e32 v25, 0xffffe780
	v_mov_b32_e32 v26, 0xc00
	v_mov_b32_e32 v27, 0x600
	v_mov_b32_e32 v28, 0x2c0000
	v_mov_b32_e32 v29, 0x1400000
	v_mov_b32_e32 v30, 0x2980000
	v_mov_b32_e32 v31, 0x900000
	v_mov_b32_e32 v32, 0x1e80000
	v_mov_b32_e32 v33, 0x700000
	v_mov_b32_e32 v34, 0x1c80000
	v_mov_b32_e32 v35, 0x100000
	v_mov_b32_e32 v36, 0x1980000
	s_branch .LBB0_379

.LBB0_693:
	v_readlane_b32 s78, v219, 30
	s_nop 3
	s_cmpk_lt_u32 s78, 0x80
	s_cbranch_scc1 .Lgu0h_skip
	v_writelane_b32 v220, s0, 0
	v_writelane_b32 v220, s1, 1
	v_writelane_b32 v220, s2, 2
	v_writelane_b32 v220, s3, 3
	v_writelane_b32 v220, s4, 4
	v_writelane_b32 v220, s5, 5
	v_writelane_b32 v220, s6, 6
	v_writelane_b32 v220, s7, 7
	v_writelane_b32 v220, s8, 8
	v_writelane_b32 v220, s9, 9
	v_writelane_b32 v220, s10, 10
	v_writelane_b32 v220, s11, 11
	v_writelane_b32 v220, s12, 12
	v_writelane_b32 v220, s13, 13
	v_writelane_b32 v220, s14, 14
	v_writelane_b32 v220, s15, 15
	v_writelane_b32 v220, s16, 16
	v_writelane_b32 v220, s17, 17
	v_writelane_b32 v220, s18, 18
	v_writelane_b32 v220, s19, 19
	v_writelane_b32 v220, s20, 20
	v_writelane_b32 v220, s21, 21
	v_writelane_b32 v220, s22, 22
	v_writelane_b32 v220, s23, 23
	v_writelane_b32 v220, s24, 24
	v_writelane_b32 v220, s25, 25
	v_writelane_b32 v220, s26, 26
	v_writelane_b32 v220, s27, 27
	v_writelane_b32 v220, s36, 28
	v_writelane_b32 v220, s37, 29
	v_writelane_b32 v220, s38, 30
	v_writelane_b32 v220, s39, 31
	v_writelane_b32 v220, s40, 32
	v_writelane_b32 v220, s41, 33
	v_writelane_b32 v220, s42, 34
	v_writelane_b32 v220, s43, 35
	v_writelane_b32 v220, s44, 36
	v_writelane_b32 v220, s45, 37
	v_writelane_b32 v220, s46, 38
	v_writelane_b32 v220, s47, 39
	v_writelane_b32 v220, s48, 40
	v_writelane_b32 v220, s49, 41
	v_writelane_b32 v220, s50, 42
	v_writelane_b32 v220, s51, 43
	s_cmpk_gt_i32 s78, 0x17f
	s_waitcnt vmcnt(0) lgkmcnt(0)
	s_barrier
	s_cbranch_scc1 .Lgu0h_BB0_1034
	s_movk_i32 s1, 0x2100
	v_and_b32_e32 v4, 56, v144
	v_mad_u32_u24 v1, v148, s1, 0
	v_lshrrev_b32_e32 v0, 5, v149
	v_and_b32_e32 v2, 31, v168
	v_mul_u32_u24_e32 v3, 0x84, v4
	v_lshlrev_b32_e32 v7, 2, v185
	s_add_i32 s0, s78, 0x1e0
	v_mov_b32_e32 v5, 0
	v_lshl_add_u32 v6, v2, 2, v1
	s_movk_i32 s1, 0x84
	v_add3_u32 v20, v1, v3, v7
	v_or_b32_e32 v21, 8, v185
	v_or_b32_e32 v22, 16, v185
	v_or_b32_e32 v23, 24, v185
	v_mov_b32_e32 v1, v0
	s_movk_i32 s2, 0x187f
	v_mov_b32_e32 v24, 0xffffe780
	v_mov_b32_e32 v25, 0xc00
	v_mov_b32_e32 v26, 0x600
	s_movk_i32 s3, 0x1ff
	s_movk_i32 s4, 0xcff
	v_lshlrev_b32_e32 v8, 2, v2
	v_lshlrev_b32_e32 v10, 1, v4
	v_mov_b32_e32 v27, 0x2c0000
	v_mov_b32_e32 v28, 0x1400000
	v_mov_b32_e32 v29, 0x2980000
	v_mov_b32_e32 v30, 0x900000
	v_mov_b32_e32 v31, 0x1e80000
	v_mov_b32_e32 v32, 0x700000
	v_mov_b32_e32 v33, 0x1c80000
	v_mov_b32_e32 v34, 0x100000
	v_mov_b32_e32 v35, 0x1980000

.Lgu0h_BB0_1032:
	s_lshl_b32 s8, s6, 1
	s_lshl_b32 s9, s5, 1
	v_or_b32_e32 v9, s8, v1
	v_or_b32_e32 v11, s9, v0
	s_add_i32 s10, s8, 4
	s_add_i32 s11, s9, 4
	s_add_i32 s12, s8, 8
	s_add_i32 s13, s9, 8
	s_add_i32 s14, s8, 12
	s_add_i32 s15, s9, 12
	s_add_i32 s16, s8, 16
	s_add_i32 s17, s9, 16
	s_add_i32 s18, s8, 20
	s_add_i32 s19, s9, 20
	s_add_i32 s20, s8, 24
	s_add_i32 s21, s9, 24
	s_add_i32 s8, s8, 28
	s_add_i32 s9, s9, 28
	v_add_u32_e32 v17, v9, v7
	v_add_u32_e32 v37, v11, v16
	v_or_b32_e32 v70, s10, v1
	v_or_b32_e32 v71, s11, v0
	v_or_b32_e32 v72, s12, v1
	v_or_b32_e32 v73, s13, v0
	v_or_b32_e32 v74, s14, v1
	v_or_b32_e32 v75, s15, v0
	v_or_b32_e32 v76, s16, v1
	v_or_b32_e32 v77, s17, v0
	v_or_b32_e32 v78, s18, v1
	v_or_b32_e32 v79, s19, v0
	v_or_b32_e32 v80, s20, v1
	v_or_b32_e32 v81, s21, v0
	v_or_b32_e32 v82, s8, v1
	v_or_b32_e32 v83, s9, v0
	v_ashrrev_i32_e32 v42, 31, v37
	v_ashrrev_i32_e32 v43, 31, v17
	v_mul_lo_u32 v84, v3, v17
	v_mad_u64_u32 v[38:39], s[8:9], v2, v17, 0
	v_mul_lo_u32 v17, v13, v37
	v_mad_u64_u32 v[40:41], s[8:9], v12, v37, 0
	v_add_u32_e32 v37, v70, v7
	v_add_u32_e32 v44, v71, v16
	v_add_u32_e32 v46, v72, v7
	v_add_u32_e32 v48, v73, v16
	v_add_u32_e32 v50, v74, v7
	v_add_u32_e32 v52, v75, v16
	v_add_u32_e32 v54, v76, v7
	v_add_u32_e32 v56, v77, v16
	v_add_u32_e32 v58, v78, v7
	v_add_u32_e32 v60, v79, v16
	v_add_u32_e32 v62, v80, v7
	v_add_u32_e32 v64, v81, v16
	v_add_u32_e32 v66, v82, v7
	v_add_u32_e32 v68, v83, v16
	v_mul_lo_u32 v85, v2, v43
	v_mul_lo_u32 v86, v12, v42
	v_ashrrev_i32_e32 v87, 31, v44
	v_ashrrev_i32_e32 v88, 31, v37
	v_ashrrev_i32_e32 v90, 31, v48
	v_ashrrev_i32_e32 v91, 31, v46
	v_ashrrev_i32_e32 v94, 31, v52
	v_ashrrev_i32_e32 v95, 31, v50
	v_ashrrev_i32_e32 v98, 31, v56
	v_ashrrev_i32_e32 v99, 31, v54
	v_ashrrev_i32_e32 v102, 31, v60
	v_ashrrev_i32_e32 v103, 31, v58
	v_ashrrev_i32_e32 v106, 31, v64
	v_ashrrev_i32_e32 v107, 31, v62
	v_ashrrev_i32_e32 v110, 31, v68
	v_ashrrev_i32_e32 v111, 31, v66
	v_mul_lo_u32 v89, v3, v37
	v_mad_u64_u32 v[42:43], s[8:9], v2, v37, 0
	v_mul_lo_u32 v37, v13, v44
	v_mad_u64_u32 v[44:45], s[8:9], v12, v44, 0
	v_mul_lo_u32 v92, v3, v46
	v_mad_u64_u32 v[46:47], s[8:9], v2, v46, 0
	v_mul_lo_u32 v93, v13, v48
	v_mad_u64_u32 v[48:49], s[8:9], v12, v48, 0
	v_mul_lo_u32 v96, v3, v50
	v_mad_u64_u32 v[50:51], s[8:9], v2, v50, 0
	v_mul_lo_u32 v97, v13, v52
	v_mad_u64_u32 v[52:53], s[8:9], v12, v52, 0
	v_mul_lo_u32 v100, v3, v54
	v_mad_u64_u32 v[54:55], s[8:9], v2, v54, 0
	v_mul_lo_u32 v101, v13, v56
	v_mad_u64_u32 v[56:57], s[8:9], v12, v56, 0
	v_mul_lo_u32 v104, v3, v58
	v_mad_u64_u32 v[58:59], s[8:9], v2, v58, 0
	v_mul_lo_u32 v105, v13, v60
	v_mad_u64_u32 v[60:61], s[8:9], v12, v60, 0
	v_mul_lo_u32 v108, v3, v62
	v_mad_u64_u32 v[62:63], s[8:9], v2, v62, 0
	v_mul_lo_u32 v109, v13, v64
	v_mad_u64_u32 v[64:65], s[8:9], v12, v64, 0
	v_mul_lo_u32 v112, v3, v66
	v_mad_u64_u32 v[66:67], s[8:9], v2, v66, 0
	v_mul_lo_u32 v113, v13, v68
	v_mad_u64_u32 v[68:69], s[8:9], v12, v68, 0
	v_add3_u32 v39, v39, v85, v84
	v_add3_u32 v41, v41, v86, v17
	v_mul_lo_u32 v17, v2, v88
	v_mul_lo_u32 v84, v12, v87
	v_mul_lo_u32 v85, v2, v91
	v_mul_lo_u32 v86, v12, v90
	v_mul_lo_u32 v87, v2, v95
	v_mul_lo_u32 v88, v12, v94
	v_mul_lo_u32 v90, v2, v99
	v_mul_lo_u32 v91, v12, v98
	v_mul_lo_u32 v94, v2, v103
	v_mul_lo_u32 v95, v12, v102
	v_mul_lo_u32 v98, v2, v107
	v_mul_lo_u32 v99, v12, v106
	v_mul_lo_u32 v102, v2, v111
	v_mul_lo_u32 v103, v12, v110
	v_lshl_add_u64 v[40:41], v[40:41], 2, v[18:19]
	v_add3_u32 v43, v43, v17, v89
	v_add3_u32 v45, v45, v84, v37
	v_add3_u32 v47, v47, v85, v92
	v_add3_u32 v49, v49, v86, v93
	v_add3_u32 v51, v51, v87, v96
	v_add3_u32 v53, v53, v88, v97
	v_add3_u32 v55, v55, v90, v100
	v_add3_u32 v57, v57, v91, v101
	v_add3_u32 v59, v59, v94, v104
	v_add3_u32 v61, v61, v95, v105
	v_add3_u32 v63, v63, v98, v108
	v_add3_u32 v65, v65, v99, v109
	v_add3_u32 v67, v67, v102, v112
	v_add3_u32 v69, v69, v103, v113
	v_lshl_add_u64 v[38:39], v[38:39], 2, v[18:19]
	v_lshl_add_u64 v[44:45], v[44:45], 2, v[18:19]
	v_lshl_add_u64 v[42:43], v[42:43], 2, v[18:19]
	v_lshl_add_u64 v[48:49], v[48:49], 2, v[18:19]
	v_lshl_add_u64 v[46:47], v[46:47], 2, v[18:19]
	v_lshl_add_u64 v[52:53], v[52:53], 2, v[18:19]
	v_lshl_add_u64 v[50:51], v[50:51], 2, v[18:19]
	v_lshl_add_u64 v[56:57], v[56:57], 2, v[18:19]
	v_lshl_add_u64 v[54:55], v[54:55], 2, v[18:19]
	v_lshl_add_u64 v[60:61], v[60:61], 2, v[18:19]
	v_lshl_add_u64 v[58:59], v[58:59], 2, v[18:19]
	v_lshl_add_u64 v[64:65], v[64:65], 2, v[18:19]
	v_lshl_add_u64 v[62:63], v[62:63], 2, v[18:19]
	v_lshl_add_u64 v[68:69], v[68:69], 2, v[18:19]
	v_lshl_add_u64 v[66:67], v[66:67], 2, v[18:19]
	global_load_dword v17, v[40:41], off
	global_load_dword v37, v[38:39], off
	global_load_dword v84, v[44:45], off
	global_load_dword v85, v[42:43], off
	global_load_dword v86, v[48:49], off
	global_load_dword v87, v[46:47], off
	global_load_dword v88, v[52:53], off
	global_load_dword v89, v[50:51], off
	global_load_dword v90, v[56:57], off
	global_load_dword v91, v[54:55], off
	global_load_dword v92, v[60:61], off
	global_load_dword v93, v[58:59], off
	global_load_dword v94, v[64:65], off
	global_load_dword v95, v[62:63], off
	global_load_dword v96, v[68:69], off
	global_load_dword v97, v[66:67], off
	s_add_i32 s5, s5, 16
	s_add_i32 s6, s6, 16
	s_add_i32 s7, s7, -16
	v_mad_u64_u32 v[38:39], s[8:9], v11, s1, v[6:7]
	s_cmp_lg_u32 s7, 0
	v_mad_u64_u32 v[40:41], s[8:9], v9, s1, v[6:7]
	v_mad_u64_u32 v[42:43], s[8:9], v71, s1, v[6:7]
	v_mad_u64_u32 v[44:45], s[8:9], v70, s1, v[6:7]
	v_mad_u64_u32 v[46:47], s[8:9], v73, s1, v[6:7]
	v_mad_u64_u32 v[48:49], s[8:9], v72, s1, v[6:7]
	v_mad_u64_u32 v[50:51], s[8:9], v75, s1, v[6:7]
	v_mad_u64_u32 v[52:53], s[8:9], v74, s1, v[6:7]
	v_mad_u64_u32 v[54:55], s[8:9], v77, s1, v[6:7]
	v_mad_u64_u32 v[56:57], s[8:9], v76, s1, v[6:7]
	v_mad_u64_u32 v[58:59], s[8:9], v79, s1, v[6:7]
	v_mad_u64_u32 v[60:61], s[8:9], v78, s1, v[6:7]
	v_mad_u64_u32 v[62:63], s[8:9], v81, s1, v[6:7]
	v_mad_u64_u32 v[64:65], s[8:9], v80, s1, v[6:7]
	v_mad_u64_u32 v[66:67], s[8:9], v83, s1, v[6:7]
	v_mad_u64_u32 v[68:69], s[8:9], v82, s1, v[6:7]
	s_waitcnt vmcnt(15)
	ds_write_b32 v38, v17
	s_waitcnt vmcnt(14)
	ds_write_b32 v40, v37
	s_waitcnt vmcnt(13)
	ds_write_b32 v42, v84
	s_waitcnt vmcnt(12)
	ds_write_b32 v44, v85
	s_waitcnt vmcnt(11)
	ds_write_b32 v46, v86
	s_waitcnt vmcnt(10)
	ds_write_b32 v48, v87
	s_waitcnt vmcnt(9)
	ds_write_b32 v50, v88
	s_waitcnt vmcnt(8)
	ds_write_b32 v52, v89
	s_waitcnt vmcnt(7)
	ds_write_b32 v54, v90
	s_waitcnt vmcnt(6)
	ds_write_b32 v56, v91
	s_waitcnt vmcnt(5)
	ds_write_b32 v58, v92
	s_waitcnt vmcnt(4)
	ds_write_b32 v60, v93
	s_waitcnt vmcnt(3)
	ds_write_b32 v62, v94
	s_waitcnt vmcnt(2)
	ds_write_b32 v64, v95
	s_waitcnt vmcnt(1)
	ds_write_b32 v66, v96
	s_waitcnt vmcnt(0)
	ds_write_b32 v68, v97
	s_cbranch_scc1 .Lgu0h_BB0_1032
	s_waitcnt lgkmcnt(0)
	v_ashrrev_i32_e32 v17, 31, v16
	v_lshl_add_u64 v[2:3], v[16:17], 1, v[14:15]
	ds_read2_b32 v[16:17], v20 offset0:33 offset1:41
	ds_read2_b32 v[18:19], v20 offset1:8
	ds_read2_b32 v[38:39], v20 offset0:66 offset1:74
	ds_read2_b32 v[40:41], v20 offset0:99 offset1:107
	ds_read2_b32 v[42:43], v20 offset0:132 offset1:140
	ds_read2_b32 v[44:45], v20 offset0:165 offset1:173
	ds_read2_b32 v[46:47], v20 offset0:198 offset1:206
	ds_read2_b32 v[48:49], v20 offset0:231 offset1:239
	v_or_b32_e32 v7, v4, v185
	v_ashrrev_i32_e32 v9, 31, v4
	v_mov_b32_e32 v11, v5
	v_mul_lo_u32 v9, v9, v36
	v_mad_u64_u32 v[50:51], s[6:7], v7, v36, 0
	v_lshl_add_u64 v[2:3], v[2:3], 0, v[10:11]
	v_add_u32_e32 v51, v51, v9
	s_waitcnt lgkmcnt(6)
	v_cvt_pk_bf16_f32 v12, v18, v16
	s_waitcnt lgkmcnt(4)
	v_cvt_pk_bf16_f32 v13, v38, v40
	s_waitcnt lgkmcnt(2)
	v_cvt_pk_bf16_f32 v14, v42, v44
	s_waitcnt lgkmcnt(0)
	v_cvt_pk_bf16_f32 v15, v46, v48
	v_lshl_add_u64 v[50:51], v[50:51], 1, v[2:3]
	global_store_dwordx4 v[50:51], v[12:15], off
	v_or_b32_e32 v7, v4, v21
	s_add_i32 s5, s0, 0x80
	v_cvt_pk_bf16_f32 v12, v19, v17
	v_cvt_pk_bf16_f32 v13, v39, v41
	v_cvt_pk_bf16_f32 v14, v43, v45
	v_cvt_pk_bf16_f32 v15, v47, v49
	v_mad_u64_u32 v[16:17], s[6:7], v7, v36, 0
	ds_read2_b32 v[18:19], v20 offset0:16 offset1:24
	ds_read2_b32 v[38:39], v20 offset0:49 offset1:57
	ds_read2_b32 v[40:41], v20 offset0:82 offset1:90
	ds_read2_b32 v[42:43], v20 offset0:115 offset1:123
	ds_read2_b32 v[44:45], v20 offset0:148 offset1:156
	ds_read2_b32 v[46:47], v20 offset0:181 offset1:189
	ds_read2_b32 v[48:49], v20 offset0:214 offset1:222
	ds_read2_b32 v[50:51], v20 offset0:247 offset1:255
	v_add_u32_e32 v17, v17, v9
	v_lshl_add_u64 v[16:17], v[16:17], 1, v[2:3]
	v_or_b32_e32 v7, v4, v22
	global_store_dwordx4 v[16:17], v[12:15], off
	v_mad_u64_u32 v[16:17], s[6:7], v7, v36, 0
	v_add_u32_e32 v17, v17, v9
	s_waitcnt lgkmcnt(6)
	v_cvt_pk_bf16_f32 v12, v18, v38
	s_waitcnt lgkmcnt(4)
	v_cvt_pk_bf16_f32 v13, v40, v42
	s_waitcnt lgkmcnt(2)
	v_cvt_pk_bf16_f32 v14, v44, v46
	s_waitcnt lgkmcnt(0)
	v_cvt_pk_bf16_f32 v15, v48, v50
	v_lshl_add_u64 v[16:17], v[16:17], 1, v[2:3]
	v_or_b32_e32 v4, v4, v23
	global_store_dwordx4 v[16:17], v[12:15], off
	v_mad_u64_u32 v[16:17], s[6:7], v4, v36, 0
	v_add_u32_e32 v17, v17, v9
	v_cvt_pk_bf16_f32 v12, v19, v39
	v_cvt_pk_bf16_f32 v13, v41, v43
	v_cvt_pk_bf16_f32 v14, v45, v47
	v_cvt_pk_bf16_f32 v15, v49, v51
	v_lshl_add_u64 v[2:3], v[16:17], 1, v[2:3]
	global_store_dwordx4 v[2:3], v[12:15], off
	s_waitcnt lgkmcnt(0)
	s_cmpk_gt_i32 s0, 0x38f
	s_mov_b32 s0, s5
	s_cbranch_scc0 .Lgu0h_BB0_1019

.LBB0_1016:
	s_cmpk_lg_i32 s58, 0x100
	s_cselect_b64 s[0:1], -1, 0
	s_cmpk_lt_u32 s78, 0x80
	s_cselect_b64 s[2:3], -1, 0
	s_or_b64 s[0:1], s[2:3], s[0:1]
	s_and_b64 vcc, exec, s[0:1]
	s_cbranch_vccnz .LBB0_1035
	s_cmpk_gt_i32 s78, 0x17f
	s_waitcnt vmcnt(0) lgkmcnt(0)
	s_barrier
	s_cbranch_scc1 .LBB0_1034
	s_movk_i32 s1, 0x2100
	v_and_b32_e32 v4, 56, v144
	v_mad_u32_u24 v1, v148, s1, 0
	v_lshrrev_b32_e32 v0, 5, v149
	v_and_b32_e32 v2, 31, v168
	v_mul_u32_u24_e32 v3, 0x84, v4
	v_lshlrev_b32_e32 v7, 2, v185
	s_add_i32 s0, s78, 0x390
	v_mov_b32_e32 v5, 0
	v_lshl_add_u32 v6, v2, 2, v1
	s_movk_i32 s1, 0x84
	v_add3_u32 v20, v1, v3, v7
	v_or_b32_e32 v21, 8, v185
	v_or_b32_e32 v22, 16, v185
	v_or_b32_e32 v23, 24, v185
	v_mov_b32_e32 v1, v0
	s_movk_i32 s2, 0x187f
	v_mov_b32_e32 v24, 0xffffe780
	v_mov_b32_e32 v25, 0xc00
	v_mov_b32_e32 v26, 0x600
	s_movk_i32 s3, 0x1ff
	s_movk_i32 s4, 0xcff
	v_lshlrev_b32_e32 v8, 2, v2
	v_lshlrev_b32_e32 v10, 1, v4
	v_mov_b32_e32 v27, 0x2c0000
	v_mov_b32_e32 v28, 0x1400000
	v_mov_b32_e32 v29, 0x2980000
	v_mov_b32_e32 v30, 0x900000
	v_mov_b32_e32 v31, 0x1e80000
	v_mov_b32_e32 v32, 0x700000
	v_mov_b32_e32 v33, 0x1c80000
	v_mov_b32_e32 v34, 0x100000
	v_mov_b32_e32 v35, 0x1980000

.LBB0_1032:
	s_lshl_b32 s8, s6, 1
	s_lshl_b32 s9, s5, 1
	v_or_b32_e32 v9, s8, v1
	v_or_b32_e32 v11, s9, v0
	s_add_i32 s10, s8, 4
	s_add_i32 s11, s9, 4
	s_add_i32 s12, s8, 8
	s_add_i32 s13, s9, 8
	s_add_i32 s14, s8, 12
	s_add_i32 s15, s9, 12
	s_add_i32 s16, s8, 16
	s_add_i32 s17, s9, 16
	s_add_i32 s18, s8, 20
	s_add_i32 s19, s9, 20
	s_add_i32 s20, s8, 24
	s_add_i32 s21, s9, 24
	s_add_i32 s8, s8, 28
	s_add_i32 s9, s9, 28
	v_add_u32_e32 v17, v9, v7
	v_add_u32_e32 v37, v11, v16
	v_or_b32_e32 v70, s10, v1
	v_or_b32_e32 v71, s11, v0
	v_or_b32_e32 v72, s12, v1
	v_or_b32_e32 v73, s13, v0
	v_or_b32_e32 v74, s14, v1
	v_or_b32_e32 v75, s15, v0
	v_or_b32_e32 v76, s16, v1
	v_or_b32_e32 v77, s17, v0
	v_or_b32_e32 v78, s18, v1
	v_or_b32_e32 v79, s19, v0
	v_or_b32_e32 v80, s20, v1
	v_or_b32_e32 v81, s21, v0
	v_or_b32_e32 v82, s8, v1
	v_or_b32_e32 v83, s9, v0
	v_ashrrev_i32_e32 v42, 31, v37
	v_ashrrev_i32_e32 v43, 31, v17
	v_mul_lo_u32 v84, v3, v17
	v_mad_u64_u32 v[38:39], s[8:9], v2, v17, 0
	v_mul_lo_u32 v17, v13, v37
	v_mad_u64_u32 v[40:41], s[8:9], v12, v37, 0
	v_add_u32_e32 v37, v70, v7
	v_add_u32_e32 v44, v71, v16
	v_add_u32_e32 v46, v72, v7
	v_add_u32_e32 v48, v73, v16
	v_add_u32_e32 v50, v74, v7
	v_add_u32_e32 v52, v75, v16
	v_add_u32_e32 v54, v76, v7
	v_add_u32_e32 v56, v77, v16
	v_add_u32_e32 v58, v78, v7
	v_add_u32_e32 v60, v79, v16
	v_add_u32_e32 v62, v80, v7
	v_add_u32_e32 v64, v81, v16
	v_add_u32_e32 v66, v82, v7
	v_add_u32_e32 v68, v83, v16
	v_mul_lo_u32 v85, v2, v43
	v_mul_lo_u32 v86, v12, v42
	v_ashrrev_i32_e32 v87, 31, v44
	v_ashrrev_i32_e32 v88, 31, v37
	v_ashrrev_i32_e32 v90, 31, v48
	v_ashrrev_i32_e32 v91, 31, v46
	v_ashrrev_i32_e32 v94, 31, v52
	v_ashrrev_i32_e32 v95, 31, v50
	v_ashrrev_i32_e32 v98, 31, v56
	v_ashrrev_i32_e32 v99, 31, v54
	v_ashrrev_i32_e32 v102, 31, v60
	v_ashrrev_i32_e32 v103, 31, v58
	v_ashrrev_i32_e32 v106, 31, v64
	v_ashrrev_i32_e32 v107, 31, v62
	v_ashrrev_i32_e32 v110, 31, v68
	v_ashrrev_i32_e32 v111, 31, v66
	v_mul_lo_u32 v89, v3, v37
	v_mad_u64_u32 v[42:43], s[8:9], v2, v37, 0
	v_mul_lo_u32 v37, v13, v44
	v_mad_u64_u32 v[44:45], s[8:9], v12, v44, 0
	v_mul_lo_u32 v92, v3, v46
	v_mad_u64_u32 v[46:47], s[8:9], v2, v46, 0
	v_mul_lo_u32 v93, v13, v48
	v_mad_u64_u32 v[48:49], s[8:9], v12, v48, 0
	v_mul_lo_u32 v96, v3, v50
	v_mad_u64_u32 v[50:51], s[8:9], v2, v50, 0
	v_mul_lo_u32 v97, v13, v52
	v_mad_u64_u32 v[52:53], s[8:9], v12, v52, 0
	v_mul_lo_u32 v100, v3, v54
	v_mad_u64_u32 v[54:55], s[8:9], v2, v54, 0
	v_mul_lo_u32 v101, v13, v56
	v_mad_u64_u32 v[56:57], s[8:9], v12, v56, 0
	v_mul_lo_u32 v104, v3, v58
	v_mad_u64_u32 v[58:59], s[8:9], v2, v58, 0
	v_mul_lo_u32 v105, v13, v60
	v_mad_u64_u32 v[60:61], s[8:9], v12, v60, 0
	v_mul_lo_u32 v108, v3, v62
	v_mad_u64_u32 v[62:63], s[8:9], v2, v62, 0
	v_mul_lo_u32 v109, v13, v64
	v_mad_u64_u32 v[64:65], s[8:9], v12, v64, 0
	v_mul_lo_u32 v112, v3, v66
	v_mad_u64_u32 v[66:67], s[8:9], v2, v66, 0
	v_mul_lo_u32 v113, v13, v68
	v_mad_u64_u32 v[68:69], s[8:9], v12, v68, 0
	v_add3_u32 v39, v39, v85, v84
	v_add3_u32 v41, v41, v86, v17
	v_mul_lo_u32 v17, v2, v88
	v_mul_lo_u32 v84, v12, v87
	v_mul_lo_u32 v85, v2, v91
	v_mul_lo_u32 v86, v12, v90
	v_mul_lo_u32 v87, v2, v95
	v_mul_lo_u32 v88, v12, v94
	v_mul_lo_u32 v90, v2, v99
	v_mul_lo_u32 v91, v12, v98
	v_mul_lo_u32 v94, v2, v103
	v_mul_lo_u32 v95, v12, v102
	v_mul_lo_u32 v98, v2, v107
	v_mul_lo_u32 v99, v12, v106
	v_mul_lo_u32 v102, v2, v111
	v_mul_lo_u32 v103, v12, v110
	v_lshl_add_u64 v[40:41], v[40:41], 2, v[18:19]
	v_add3_u32 v43, v43, v17, v89
	v_add3_u32 v45, v45, v84, v37
	v_add3_u32 v47, v47, v85, v92
	v_add3_u32 v49, v49, v86, v93
	v_add3_u32 v51, v51, v87, v96
	v_add3_u32 v53, v53, v88, v97
	v_add3_u32 v55, v55, v90, v100
	v_add3_u32 v57, v57, v91, v101
	v_add3_u32 v59, v59, v94, v104
	v_add3_u32 v61, v61, v95, v105
	v_add3_u32 v63, v63, v98, v108
	v_add3_u32 v65, v65, v99, v109
	v_add3_u32 v67, v67, v102, v112
	v_add3_u32 v69, v69, v103, v113
	v_lshl_add_u64 v[38:39], v[38:39], 2, v[18:19]
	v_lshl_add_u64 v[44:45], v[44:45], 2, v[18:19]
	v_lshl_add_u64 v[42:43], v[42:43], 2, v[18:19]
	v_lshl_add_u64 v[48:49], v[48:49], 2, v[18:19]
	v_lshl_add_u64 v[46:47], v[46:47], 2, v[18:19]
	v_lshl_add_u64 v[52:53], v[52:53], 2, v[18:19]
	v_lshl_add_u64 v[50:51], v[50:51], 2, v[18:19]
	v_lshl_add_u64 v[56:57], v[56:57], 2, v[18:19]
	v_lshl_add_u64 v[54:55], v[54:55], 2, v[18:19]
	v_lshl_add_u64 v[60:61], v[60:61], 2, v[18:19]
	v_lshl_add_u64 v[58:59], v[58:59], 2, v[18:19]
	v_lshl_add_u64 v[64:65], v[64:65], 2, v[18:19]
	v_lshl_add_u64 v[62:63], v[62:63], 2, v[18:19]
	v_lshl_add_u64 v[68:69], v[68:69], 2, v[18:19]
	v_lshl_add_u64 v[66:67], v[66:67], 2, v[18:19]
	global_load_dword v17, v[40:41], off
	global_load_dword v37, v[38:39], off
	global_load_dword v84, v[44:45], off
	global_load_dword v85, v[42:43], off
	global_load_dword v86, v[48:49], off
	global_load_dword v87, v[46:47], off
	global_load_dword v88, v[52:53], off
	global_load_dword v89, v[50:51], off
	global_load_dword v90, v[56:57], off
	global_load_dword v91, v[54:55], off
	global_load_dword v92, v[60:61], off
	global_load_dword v93, v[58:59], off
	global_load_dword v94, v[64:65], off
	global_load_dword v95, v[62:63], off
	global_load_dword v96, v[68:69], off
	global_load_dword v97, v[66:67], off
	s_add_i32 s5, s5, 16
	s_add_i32 s6, s6, 16
	s_add_i32 s7, s7, -16
	v_mad_u64_u32 v[38:39], s[8:9], v11, s1, v[6:7]
	s_cmp_lg_u32 s7, 0
	v_mad_u64_u32 v[40:41], s[8:9], v9, s1, v[6:7]
	v_mad_u64_u32 v[42:43], s[8:9], v71, s1, v[6:7]
	v_mad_u64_u32 v[44:45], s[8:9], v70, s1, v[6:7]
	v_mad_u64_u32 v[46:47], s[8:9], v73, s1, v[6:7]
	v_mad_u64_u32 v[48:49], s[8:9], v72, s1, v[6:7]
	v_mad_u64_u32 v[50:51], s[8:9], v75, s1, v[6:7]
	v_mad_u64_u32 v[52:53], s[8:9], v74, s1, v[6:7]
	v_mad_u64_u32 v[54:55], s[8:9], v77, s1, v[6:7]
	v_mad_u64_u32 v[56:57], s[8:9], v76, s1, v[6:7]
	v_mad_u64_u32 v[58:59], s[8:9], v79, s1, v[6:7]
	v_mad_u64_u32 v[60:61], s[8:9], v78, s1, v[6:7]
	v_mad_u64_u32 v[62:63], s[8:9], v81, s1, v[6:7]
	v_mad_u64_u32 v[64:65], s[8:9], v80, s1, v[6:7]
	v_mad_u64_u32 v[66:67], s[8:9], v83, s1, v[6:7]
	v_mad_u64_u32 v[68:69], s[8:9], v82, s1, v[6:7]
	s_waitcnt vmcnt(15)
	ds_write_b32 v38, v17
	s_waitcnt vmcnt(14)
	ds_write_b32 v40, v37
	s_waitcnt vmcnt(13)
	ds_write_b32 v42, v84
	s_waitcnt vmcnt(12)
	ds_write_b32 v44, v85
	s_waitcnt vmcnt(11)
	ds_write_b32 v46, v86
	s_waitcnt vmcnt(10)
	ds_write_b32 v48, v87
	s_waitcnt vmcnt(9)
	ds_write_b32 v50, v88
	s_waitcnt vmcnt(8)
	ds_write_b32 v52, v89
	s_waitcnt vmcnt(7)
	ds_write_b32 v54, v90
	s_waitcnt vmcnt(6)
	ds_write_b32 v56, v91
	s_waitcnt vmcnt(5)
	ds_write_b32 v58, v92
	s_waitcnt vmcnt(4)
	ds_write_b32 v60, v93
	s_waitcnt vmcnt(3)
	ds_write_b32 v62, v94
	s_waitcnt vmcnt(2)
	ds_write_b32 v64, v95
	s_waitcnt vmcnt(1)
	ds_write_b32 v66, v96
	s_waitcnt vmcnt(0)
	ds_write_b32 v68, v97
	s_cbranch_scc1 .LBB0_1032
	s_waitcnt lgkmcnt(0)
	v_ashrrev_i32_e32 v17, 31, v16
	v_lshl_add_u64 v[2:3], v[16:17], 1, v[14:15]
	ds_read2_b32 v[16:17], v20 offset0:33 offset1:41
	ds_read2_b32 v[18:19], v20 offset1:8
	ds_read2_b32 v[38:39], v20 offset0:66 offset1:74
	ds_read2_b32 v[40:41], v20 offset0:99 offset1:107
	ds_read2_b32 v[42:43], v20 offset0:132 offset1:140
	ds_read2_b32 v[44:45], v20 offset0:165 offset1:173
	ds_read2_b32 v[46:47], v20 offset0:198 offset1:206
	ds_read2_b32 v[48:49], v20 offset0:231 offset1:239
	v_or_b32_e32 v7, v4, v185
	v_ashrrev_i32_e32 v9, 31, v4
	v_mov_b32_e32 v11, v5
	v_mul_lo_u32 v9, v9, v36
	v_mad_u64_u32 v[50:51], s[6:7], v7, v36, 0
	v_lshl_add_u64 v[2:3], v[2:3], 0, v[10:11]
	v_add_u32_e32 v51, v51, v9
	s_waitcnt lgkmcnt(6)
	v_cvt_pk_bf16_f32 v12, v18, v16
	s_waitcnt lgkmcnt(4)
	v_cvt_pk_bf16_f32 v13, v38, v40
	s_waitcnt lgkmcnt(2)
	v_cvt_pk_bf16_f32 v14, v42, v44
	s_waitcnt lgkmcnt(0)
	v_cvt_pk_bf16_f32 v15, v46, v48
	v_lshl_add_u64 v[50:51], v[50:51], 1, v[2:3]
	global_store_dwordx4 v[50:51], v[12:15], off
	v_or_b32_e32 v7, v4, v21
	s_add_i32 s5, s0, 0x80
	v_cvt_pk_bf16_f32 v12, v19, v17
	v_cvt_pk_bf16_f32 v13, v39, v41
	v_cvt_pk_bf16_f32 v14, v43, v45
	v_cvt_pk_bf16_f32 v15, v47, v49
	v_mad_u64_u32 v[16:17], s[6:7], v7, v36, 0
	ds_read2_b32 v[18:19], v20 offset0:16 offset1:24
	ds_read2_b32 v[38:39], v20 offset0:49 offset1:57
	ds_read2_b32 v[40:41], v20 offset0:82 offset1:90
	ds_read2_b32 v[42:43], v20 offset0:115 offset1:123
	ds_read2_b32 v[44:45], v20 offset0:148 offset1:156
	ds_read2_b32 v[46:47], v20 offset0:181 offset1:189
	ds_read2_b32 v[48:49], v20 offset0:214 offset1:222
	ds_read2_b32 v[50:51], v20 offset0:247 offset1:255
	v_add_u32_e32 v17, v17, v9
	v_lshl_add_u64 v[16:17], v[16:17], 1, v[2:3]
	v_or_b32_e32 v7, v4, v22
	global_store_dwordx4 v[16:17], v[12:15], off
	v_mad_u64_u32 v[16:17], s[6:7], v7, v36, 0
	v_add_u32_e32 v17, v17, v9
	s_waitcnt lgkmcnt(6)
	v_cvt_pk_bf16_f32 v12, v18, v38
	s_waitcnt lgkmcnt(4)
	v_cvt_pk_bf16_f32 v13, v40, v42
	s_waitcnt lgkmcnt(2)
	v_cvt_pk_bf16_f32 v14, v44, v46
	s_waitcnt lgkmcnt(0)
	v_cvt_pk_bf16_f32 v15, v48, v50
	v_lshl_add_u64 v[16:17], v[16:17], 1, v[2:3]
	v_or_b32_e32 v4, v4, v23
	global_store_dwordx4 v[16:17], v[12:15], off
	v_mad_u64_u32 v[16:17], s[6:7], v4, v36, 0
	v_add_u32_e32 v17, v17, v9
	v_cvt_pk_bf16_f32 v12, v19, v39
	v_cvt_pk_bf16_f32 v13, v41, v43
	v_cvt_pk_bf16_f32 v14, v45, v47
	v_cvt_pk_bf16_f32 v15, v49, v51
	v_lshl_add_u64 v[2:3], v[16:17], 1, v[2:3]
	global_store_dwordx4 v[2:3], v[12:15], off
	s_waitcnt lgkmcnt(0)
	s_cmpk_gt_i32 s0, 0x53f
	s_mov_b32 s0, s5
	s_cbranch_scc0 .LBB0_1019
